# memory cross-attention Q prologue: 32 gain loads through an 8-deep prefetch ring with counted vmcnt (on v48)
# speedup vs baseline: 1.0069x; 1.0017x over previous
; __device__ __forceinline__ float shx(float v, int m, int lane) { return __int_as_float(__builtin_amdgcn_ds_bpermute((lane ^ m) << 2, __float_as_int(v))); }
; __device__ __forceinline__ float bf_lo(unsigned u) { return __uint_as_float(u << 16); }
; __device__ __forceinline__ float bf_hi(unsigned u) { return __uint_as_float(u & 0xffff0000u); }
; template <int DQK, bool MLA> ...
;     ...
;         const bf16_t* qrow = Q + (size_t)(wid * 32 + r32) * qpitch + hi * 8;
;         u32x4 raw[KS];
; #pragma unroll
;         for (int d0 = 0; d0 < KS; ++d0) raw[d0] = *(const u32x4*)(qrow + d0 * 16);
;         constexpr int NS1 = MLA ? 8 : KS;
;         float s1 = 0.f, s2 = 0.f;
; #pragma unroll
;         for (int d0 = 0; d0 < KS; ++d0)
; #pragma unroll
;             for (int e = 0; e < 4; ++e) { const float a = bf_lo(raw[d0][e]), b = bf_hi(raw[d0][e]); if (d0 < NS1) s1 += a * a + b * b; else s2 += a * a + b * b; }
;         s1 += shx(s1, 32, lane); s2 += shx(s2, 32, lane);
.LBB0_1063:
	s_lshl_b32 s3, s47, 5
	s_and_b32 s10, s3, 0xffffff00
	s_ashr_i32 s11, s10, 31
	s_and_b32 s22, s47, 1
	s_bfe_u32 s2, s47, 0x20001
	s_lshl_b64 s[4:5], s[10:11], 11
	v_readlane_b32 s30, v252, 52
	v_readlane_b32 s31, v252, 53
	s_add_u32 s3, s30, s4
	s_addc_u32 s4, s31, s5
	s_lshl_b32 s5, s2, 9
	v_mbcnt_lo_u32_b32 v56, -1, 0
	v_mbcnt_hi_u32_b32 v56, -1, v56
	s_add_u32 s34, s3, s5
	v_and_b32_e32 v54, 31, v56
	v_or_b32_e32 v0, s28, v54
	v_mov_b32_e32 v1, v192
	s_addc_u32 s35, s4, 0
	v_bfe_u32 v55, v56, 5, 1
	v_lshlrev_b64 v[188:189], 11, v[0:1]
	v_lshl_add_u64 v[0:1], s[34:35], 0, v[188:189]
	v_lshlrev_b32_e32 v52, 4, v55
	v_mov_b32_e32 v53, v192
	v_lshl_add_u64 v[0:1], v[0:1], 0, v[52:53]
	global_load_dwordx4 v[58:61], v[0:1], off
	global_load_dwordx4 v[62:65], v[0:1], off offset:32
	global_load_dwordx4 v[66:69], v[0:1], off offset:64
	global_load_dwordx4 v[48:51], v[0:1], off offset:96
	global_load_dwordx4 v[44:47], v[0:1], off offset:128
	global_load_dwordx4 v[40:43], v[0:1], off offset:160
	global_load_dwordx4 v[36:39], v[0:1], off offset:192
	global_load_dwordx4 v[32:35], v[0:1], off offset:224
	global_load_dwordx4 v[28:31], v[0:1], off offset:256
	global_load_dwordx4 v[24:27], v[0:1], off offset:288
	global_load_dwordx4 v[20:23], v[0:1], off offset:320
	global_load_dwordx4 v[16:19], v[0:1], off offset:352
	global_load_dwordx4 v[12:15], v[0:1], off offset:384
	global_load_dwordx4 v[8:11], v[0:1], off offset:416
	global_load_dwordx4 v[4:7], v[0:1], off offset:448
	s_nop 0
	global_load_dwordx4 v[0:3], v[0:1], off offset:480
	v_and_b32_e32 v142, 63, v56
	s_add_u32 s4, s6, s5
	s_addc_u32 s5, s7, 0
	s_lshl_b32 s3, s2, 1
	s_or_b32 s3, s3, s36
	s_or_b32 s3, s3, s22
	s_mul_i32 s68, s3, 0x9000
	s_lshl_b64 s[30:31], s[68:69], 1
	v_readlane_b32 s3, v253, 58
	s_add_u32 s30, s3, s30
	v_readlane_b32 s3, v253, 59
	s_addc_u32 s31, s3, s31
	s_movk_i32 s3, 0x80
	s_waitcnt vmcnt(15)
	v_and_b32_e32 v96, 0xffff0000, v58
	v_and_b32_e32 v98, 0xffff0000, v59
	v_lshlrev_b32_e32 v97, 16, v58
	v_mul_f32_e32 v53, v96, v96
	v_lshlrev_b32_e32 v99, 16, v59
	v_mul_f32_e32 v57, v98, v98
	v_fmac_f32_e32 v53, v97, v97
	v_fmac_f32_e32 v57, v99, v99
	v_and_b32_e32 v138, 0xffff0000, v60
	v_add_f32_e32 v53, v53, v57
	v_lshlrev_b32_e32 v139, 16, v60
	v_mul_f32_e32 v57, v138, v138
	v_fmac_f32_e32 v57, v139, v139
	v_and_b32_e32 v140, 0xffff0000, v61
	v_add_f32_e32 v53, v57, v53
	v_lshlrev_b32_e32 v141, 16, v61
	v_mul_f32_e32 v57, v140, v140
	v_fmac_f32_e32 v57, v141, v141
	s_waitcnt vmcnt(14)
	v_and_b32_e32 v100, 0xffff0000, v62
	v_add_f32_e32 v53, v57, v53
	v_lshlrev_b32_e32 v101, 16, v62
	v_mul_f32_e32 v57, v100, v100
	v_fmac_f32_e32 v57, v101, v101
	v_and_b32_e32 v102, 0xffff0000, v63
	v_add_f32_e32 v53, v57, v53
	v_lshlrev_b32_e32 v103, 16, v63
	v_mul_f32_e32 v57, v102, v102
	v_fmac_f32_e32 v57, v103, v103
	v_and_b32_e32 v134, 0xffff0000, v64
	v_add_f32_e32 v53, v57, v53
	v_lshlrev_b32_e32 v135, 16, v64
	v_mul_f32_e32 v57, v134, v134
	v_fmac_f32_e32 v57, v135, v135
	v_and_b32_e32 v136, 0xffff0000, v65
	v_add_f32_e32 v53, v57, v53
	v_lshlrev_b32_e32 v137, 16, v65
	v_mul_f32_e32 v57, v136, v136
	v_fmac_f32_e32 v57, v137, v137
	s_waitcnt vmcnt(13)
	v_and_b32_e32 v104, 0xffff0000, v66
	v_add_f32_e32 v53, v57, v53
	v_lshlrev_b32_e32 v105, 16, v66
	v_mul_f32_e32 v57, v104, v104
	v_fmac_f32_e32 v57, v105, v105
	v_and_b32_e32 v106, 0xffff0000, v67
	v_add_f32_e32 v53, v57, v53
	v_lshlrev_b32_e32 v107, 16, v67
	v_mul_f32_e32 v57, v106, v106
	v_fmac_f32_e32 v57, v107, v107
	v_and_b32_e32 v111, 0xffff0000, v68
	v_add_f32_e32 v53, v57, v53
	v_lshlrev_b32_e32 v126, 16, v68
	v_mul_f32_e32 v57, v111, v111
	v_fmac_f32_e32 v57, v126, v126
	v_and_b32_e32 v127, 0xffff0000, v69
	v_add_f32_e32 v53, v57, v53
	v_lshlrev_b32_e32 v128, 16, v69
	v_mul_f32_e32 v57, v127, v127
	s_waitcnt vmcnt(12)
	v_and_b32_e32 v108, 0xffff0000, v48
	v_fmac_f32_e32 v57, v128, v128
	v_lshlrev_b32_e32 v109, 16, v48
	v_mul_f32_e32 v48, v108, v108
	v_and_b32_e32 v129, 0xffff0000, v49
	v_add_f32_e32 v53, v57, v53
	v_fmac_f32_e32 v48, v109, v109
	v_lshlrev_b32_e32 v110, 16, v49
	v_mul_f32_e32 v49, v129, v129
	v_add_f32_e32 v48, v48, v53
	v_fmac_f32_e32 v49, v110, v110
	v_and_b32_e32 v130, 0xffff0000, v50
	v_add_f32_e32 v48, v49, v48
	v_lshlrev_b32_e32 v131, 16, v50
	v_mul_f32_e32 v49, v130, v130
	v_fmac_f32_e32 v49, v131, v131
	v_and_b32_e32 v132, 0xffff0000, v51
	v_add_f32_e32 v48, v49, v48
	v_lshlrev_b32_e32 v133, 16, v51
	v_mul_f32_e32 v49, v132, v132
	s_waitcnt vmcnt(11)
	v_and_b32_e32 v112, 0xffff0000, v44
	v_fmac_f32_e32 v49, v133, v133
	v_lshlrev_b32_e32 v113, 16, v44
	v_mul_f32_e32 v44, v112, v112
	v_and_b32_e32 v114, 0xffff0000, v45
	v_add_f32_e32 v48, v49, v48
	v_fmac_f32_e32 v44, v113, v113
	v_lshlrev_b32_e32 v115, 16, v45
	v_mul_f32_e32 v45, v114, v114
	v_add_f32_e32 v44, v44, v48
	v_fmac_f32_e32 v45, v115, v115
	v_and_b32_e32 v116, 0xffff0000, v46
	v_add_f32_e32 v44, v45, v44
	v_lshlrev_b32_e32 v123, 16, v46
	v_mul_f32_e32 v45, v116, v116
	v_fmac_f32_e32 v45, v123, v123
	v_and_b32_e32 v124, 0xffff0000, v47
	v_add_f32_e32 v44, v45, v44
	v_lshlrev_b32_e32 v125, 16, v47
	v_mul_f32_e32 v45, v124, v124
	s_waitcnt vmcnt(10)
	v_and_b32_e32 v94, 0xffff0000, v40
	v_fmac_f32_e32 v45, v125, v125
	v_lshlrev_b32_e32 v95, 16, v40
	v_mul_f32_e32 v40, v94, v94
	v_and_b32_e32 v117, 0xffff0000, v41
	v_add_f32_e32 v44, v45, v44
	v_fmac_f32_e32 v40, v95, v95
	v_lshlrev_b32_e32 v118, 16, v41
	v_mul_f32_e32 v41, v117, v117
	v_add_f32_e32 v40, v40, v44
	v_fmac_f32_e32 v41, v118, v118
	v_and_b32_e32 v119, 0xffff0000, v42
	v_add_f32_e32 v40, v41, v40
	v_lshlrev_b32_e32 v120, 16, v42
	v_mul_f32_e32 v41, v119, v119
	v_fmac_f32_e32 v41, v120, v120
	v_and_b32_e32 v121, 0xffff0000, v43
	v_add_f32_e32 v40, v41, v40
	v_lshlrev_b32_e32 v122, 16, v43
	v_mul_f32_e32 v41, v121, v121
	s_waitcnt vmcnt(9)
; __device__ __forceinline__ float bf_lo(unsigned u) { return __uint_as_float(u << 16); }
; __device__ __forceinline__ float bf_hi(unsigned u) { return __uint_as_float(u & 0xffff0000u); }
; template <int DQK, bool MLA> ...
;     ...
;         float s1 = 0.f, s2 = 0.f;
; #pragma unroll
;         for (int d0 = 0; d0 < KS; ++d0)
; #pragma unroll
;             for (int e = 0; e < 4; ++e) { const float a = bf_lo(raw[d0][e]), b = bf_hi(raw[d0][e]); if (d0 < NS1) s1 += a * a + b * b; else s2 += a * a + b * b; }
	v_and_b32_e32 v86, 0xffff0000, v36
	v_fmac_f32_e32 v41, v122, v122
	v_lshlrev_b32_e32 v87, 16, v36
	v_mul_f32_e32 v36, v86, v86
	v_and_b32_e32 v88, 0xffff0000, v37
	v_add_f32_e32 v40, v41, v40
	v_fmac_f32_e32 v36, v87, v87
	v_lshlrev_b32_e32 v89, 16, v37
	v_mul_f32_e32 v37, v88, v88
	v_add_f32_e32 v36, v36, v40
	v_fmac_f32_e32 v37, v89, v89
	v_and_b32_e32 v90, 0xffff0000, v38
	v_add_f32_e32 v36, v37, v36
	v_lshlrev_b32_e32 v91, 16, v38
	v_mul_f32_e32 v37, v90, v90
	v_fmac_f32_e32 v37, v91, v91
	v_and_b32_e32 v92, 0xffff0000, v39
	v_add_f32_e32 v36, v37, v36
	v_lshlrev_b32_e32 v93, 16, v39
	v_mul_f32_e32 v37, v92, v92
	s_waitcnt vmcnt(8)
	v_and_b32_e32 v78, 0xffff0000, v32
	v_fmac_f32_e32 v37, v93, v93
	v_lshlrev_b32_e32 v79, 16, v32
	v_mul_f32_e32 v32, v78, v78
	v_and_b32_e32 v80, 0xffff0000, v33
	v_add_f32_e32 v36, v37, v36
	v_fmac_f32_e32 v32, v79, v79
	v_lshlrev_b32_e32 v81, 16, v33
	v_mul_f32_e32 v33, v80, v80
	v_add_f32_e32 v32, v32, v36
	v_fmac_f32_e32 v33, v81, v81
	v_and_b32_e32 v82, 0xffff0000, v34
	v_add_f32_e32 v32, v33, v32
	v_lshlrev_b32_e32 v83, 16, v34
	v_mul_f32_e32 v33, v82, v82
	v_fmac_f32_e32 v33, v83, v83
	v_and_b32_e32 v84, 0xffff0000, v35
	v_add_f32_e32 v32, v33, v32
	v_lshlrev_b32_e32 v85, 16, v35
	v_mul_f32_e32 v33, v84, v84
	s_waitcnt vmcnt(7)
	v_and_b32_e32 v70, 0xffff0000, v28
	v_fmac_f32_e32 v33, v85, v85
	v_lshlrev_b32_e32 v71, 16, v28
	v_mul_f32_e32 v28, v70, v70
	v_and_b32_e32 v72, 0xffff0000, v29
	v_add_f32_e32 v32, v33, v32
	v_fmac_f32_e32 v28, v71, v71
	v_lshlrev_b32_e32 v73, 16, v29
	v_mul_f32_e32 v29, v72, v72
	v_add_f32_e32 v28, v28, v32
	v_fmac_f32_e32 v29, v73, v73
	v_and_b32_e32 v74, 0xffff0000, v30
	v_add_f32_e32 v28, v29, v28
	v_lshlrev_b32_e32 v75, 16, v30
	v_mul_f32_e32 v29, v74, v74
	v_fmac_f32_e32 v29, v75, v75
	v_and_b32_e32 v76, 0xffff0000, v31
	v_add_f32_e32 v28, v29, v28
	v_lshlrev_b32_e32 v77, 16, v31
	v_mul_f32_e32 v29, v76, v76
	s_waitcnt vmcnt(6)
	v_and_b32_e32 v62, 0xffff0000, v24
	v_fmac_f32_e32 v29, v77, v77
	v_lshlrev_b32_e32 v63, 16, v24
	v_mul_f32_e32 v24, v62, v62
	v_and_b32_e32 v64, 0xffff0000, v25
	v_add_f32_e32 v28, v29, v28
	v_fmac_f32_e32 v24, v63, v63
	v_lshlrev_b32_e32 v65, 16, v25
	v_mul_f32_e32 v25, v64, v64
	v_add_f32_e32 v24, v24, v28
	v_fmac_f32_e32 v25, v65, v65
	v_and_b32_e32 v66, 0xffff0000, v26
	v_add_f32_e32 v24, v25, v24
	v_lshlrev_b32_e32 v67, 16, v26
	v_mul_f32_e32 v25, v66, v66
	v_fmac_f32_e32 v25, v67, v67
	v_and_b32_e32 v68, 0xffff0000, v27
	v_add_f32_e32 v24, v25, v24
	v_lshlrev_b32_e32 v69, 16, v27
	v_mul_f32_e32 v25, v68, v68
	s_waitcnt vmcnt(5)
	v_and_b32_e32 v50, 0xffff0000, v20
	v_fmac_f32_e32 v25, v69, v69
	v_lshlrev_b32_e32 v51, 16, v20
	v_mul_f32_e32 v20, v50, v50
	v_and_b32_e32 v53, 0xffff0000, v21
	v_add_f32_e32 v24, v25, v24
	v_fmac_f32_e32 v20, v51, v51
	v_lshlrev_b32_e32 v57, 16, v21
	v_mul_f32_e32 v21, v53, v53
	v_add_f32_e32 v20, v20, v24
	v_fmac_f32_e32 v21, v57, v57
	v_and_b32_e32 v58, 0xffff0000, v22
	v_add_f32_e32 v20, v21, v20
	v_lshlrev_b32_e32 v59, 16, v22
	v_mul_f32_e32 v21, v58, v58
	v_fmac_f32_e32 v21, v59, v59
	v_and_b32_e32 v60, 0xffff0000, v23
	v_add_f32_e32 v20, v21, v20
	v_lshlrev_b32_e32 v61, 16, v23
	v_mul_f32_e32 v21, v60, v60
	s_waitcnt vmcnt(4)
	v_and_b32_e32 v42, 0xffff0000, v16
	v_fmac_f32_e32 v21, v61, v61
	v_lshlrev_b32_e32 v43, 16, v16
	v_mul_f32_e32 v16, v42, v42
	v_and_b32_e32 v44, 0xffff0000, v17
	v_add_f32_e32 v20, v21, v20
	v_fmac_f32_e32 v16, v43, v43
	v_lshlrev_b32_e32 v45, 16, v17
	v_mul_f32_e32 v17, v44, v44
	v_add_f32_e32 v16, v16, v20
	v_fmac_f32_e32 v17, v45, v45
	v_and_b32_e32 v46, 0xffff0000, v18
	v_add_f32_e32 v16, v17, v16
	v_lshlrev_b32_e32 v47, 16, v18
	v_mul_f32_e32 v17, v46, v46
	v_fmac_f32_e32 v17, v47, v47
	v_and_b32_e32 v48, 0xffff0000, v19
	v_add_f32_e32 v16, v17, v16
	v_lshlrev_b32_e32 v49, 16, v19
	v_mul_f32_e32 v17, v48, v48
	s_waitcnt vmcnt(3)
	v_and_b32_e32 v33, 0xffff0000, v12
	v_fmac_f32_e32 v17, v49, v49
	v_lshlrev_b32_e32 v34, 16, v12
	v_mul_f32_e32 v12, v33, v33
	v_and_b32_e32 v35, 0xffff0000, v13
	v_add_f32_e32 v16, v17, v16
	v_fmac_f32_e32 v12, v34, v34
	v_lshlrev_b32_e32 v36, 16, v13
	v_mul_f32_e32 v13, v35, v35
	v_add_f32_e32 v12, v12, v16
	v_fmac_f32_e32 v13, v36, v36
	v_and_b32_e32 v37, 0xffff0000, v14
	v_add_f32_e32 v12, v13, v12
	v_lshlrev_b32_e32 v38, 16, v14
	v_mul_f32_e32 v13, v37, v37
	v_fmac_f32_e32 v13, v38, v38
	v_and_b32_e32 v39, 0xffff0000, v15
	v_add_f32_e32 v12, v13, v12
	v_lshlrev_b32_e32 v40, 16, v15
	v_mul_f32_e32 v13, v39, v39
	s_waitcnt vmcnt(2)
	v_and_b32_e32 v25, 0xffff0000, v8
	v_fmac_f32_e32 v13, v40, v40
	v_lshlrev_b32_e32 v29, 16, v8
	v_mul_f32_e32 v8, v25, v25
	v_and_b32_e32 v26, 0xffff0000, v9
	v_add_f32_e32 v12, v13, v12
	v_fmac_f32_e32 v8, v29, v29
	v_lshlrev_b32_e32 v30, 16, v9
	v_mul_f32_e32 v9, v26, v26
	v_add_f32_e32 v8, v8, v12
	v_fmac_f32_e32 v9, v30, v30
	v_and_b32_e32 v27, 0xffff0000, v10
	v_add_f32_e32 v8, v9, v8
	v_lshlrev_b32_e32 v31, 16, v10
	v_mul_f32_e32 v9, v27, v27
	v_fmac_f32_e32 v9, v31, v31
	v_and_b32_e32 v28, 0xffff0000, v11
	v_add_f32_e32 v8, v9, v8
	v_lshlrev_b32_e32 v32, 16, v11
	v_mul_f32_e32 v9, v28, v28
	s_waitcnt vmcnt(1)
	v_and_b32_e32 v17, 0xffff0000, v4
	v_fmac_f32_e32 v9, v32, v32
	v_lshlrev_b32_e32 v21, 16, v4
	v_mul_f32_e32 v4, v17, v17
	v_and_b32_e32 v18, 0xffff0000, v5
	v_add_f32_e32 v8, v9, v8
	v_fmac_f32_e32 v4, v21, v21
	v_lshlrev_b32_e32 v22, 16, v5
	v_mul_f32_e32 v5, v18, v18
	v_add_f32_e32 v4, v4, v8
	v_fmac_f32_e32 v5, v22, v22
	v_and_b32_e32 v19, 0xffff0000, v6
	v_add_f32_e32 v4, v5, v4
	v_lshlrev_b32_e32 v23, 16, v6
	v_mul_f32_e32 v5, v19, v19
	v_fmac_f32_e32 v5, v23, v23
	v_and_b32_e32 v20, 0xffff0000, v7
	v_add_f32_e32 v4, v5, v4
	v_lshlrev_b32_e32 v24, 16, v7
	v_mul_f32_e32 v5, v20, v20
	s_waitcnt vmcnt(0)
; __device__ __forceinline__ float shx(float v, int m, int lane) { return __int_as_float(__builtin_amdgcn_ds_bpermute((lane ^ m) << 2, __float_as_int(v))); }
; __device__ __forceinline__ float bf_lo(unsigned u) { return __uint_as_float(u << 16); }
; __device__ __forceinline__ float bf_hi(unsigned u) { return __uint_as_float(u & 0xffff0000u); }
; __device__ __forceinline__ unsigned pk(float lo, float hi) { unsigned r; asm("s_nop 0\n\tv_cvt_pk_bf16_f32 %0, %1, %2" : "=v"(r) : "v"(lo), "v"(hi)); return r; }
; template <int DQK, bool MLA> ...
;     ...
;         s1 += shx(s1, 32, lane); s2 += shx(s2, 32, lane);
;         const float rs1 = __builtin_amdgcn_rsqf(s1 * (MLA ? (1.f / 128.f) : (1.f / 256.f)) + EPS) * qscale;
; #pragma unroll
;         for (int d0 = 0; d0 < NS1; ++d0) {
;             const f32x4 ga = *(const f32x4*)(g1 + d0 * 16 + hi * 8), gb = *(const f32x4*)(g1 + d0 * 16 + hi * 8 + 4); u32x4 o;
;             o.x = pk(bf_lo(raw[d0].x) * rs1 * ga[0], bf_hi(raw[d0].x) * rs1 * ga[1]); o.y = pk(bf_lo(raw[d0].y) * rs1 * ga[2], bf_hi(raw[d0].y) * rs1 * ga[3]);
;             o.z = pk(bf_lo(raw[d0].z) * rs1 * gb[0], bf_hi(raw[d0].z) * rs1 * gb[1]); o.w = pk(bf_lo(raw[d0].w) * rs1 * gb[2], bf_hi(raw[d0].w) * rs1 * gb[3]);
;             qf[d0] = __builtin_bit_cast(bf16x8, o);
;         }
	v_and_b32_e32 v13, 0xffff0000, v1
	v_and_b32_e32 v12, 0xffff0000, v0
	v_fmac_f32_e32 v5, v24, v24
	v_lshlrev_b32_e32 v15, 16, v1
	v_lshlrev_b32_e32 v14, 16, v0
	v_pk_mul_f32 v[0:1], v[12:13], v[12:13]
	v_add_f32_e32 v4, v5, v4
	v_pk_fma_f32 v[0:1], v[14:15], v[14:15], v[0:1]
	v_and_b32_e32 v9, 0xffff0000, v3
	v_add_f32_e32 v0, v0, v4
	v_and_b32_e32 v8, 0xffff0000, v2
	v_add_f32_e32 v4, v1, v0
	v_lshlrev_b32_e32 v11, 16, v3
	v_lshlrev_b32_e32 v10, 16, v2
	v_pk_mul_f32 v[0:1], v[8:9], v[8:9]
	v_and_b32_e32 v41, 32, v56
	v_pk_fma_f32 v[0:1], v[10:11], v[10:11], v[0:1]
	s_nop 0
	v_add_f32_e32 v0, v0, v4
	v_add_f32_e32 v0, v1, v0
	v_lshlrev_b32_e32 v1, 2, v142
	v_xor_b32_e32 v193, 0x80, v1
	ds_bpermute_b32 v1, v193, v0
	s_waitcnt lgkmcnt(0)
	v_add_f32_e32 v0, v0, v1
	v_fmamk_f32 v0, v0, 0x3b800000, v241
	v_rsq_f32_e32 v0, v0
	s_nop 0
	v_mul_f32_e32 v16, 0x3db8aa3b, v0
	global_load_dwordx4 v[156:159], v41, s[16:17] offset:16
	global_load_dwordx4 v[160:163], v41, s[16:17]
	global_load_dwordx4 v[164:167], v41, s[16:17] offset:80
	global_load_dwordx4 v[168:171], v41, s[16:17] offset:64
	global_load_dwordx4 v[172:175], v41, s[16:17] offset:144
	global_load_dwordx4 v[176:179], v41, s[16:17] offset:128
	global_load_dwordx4 v[180:183], v41, s[16:17] offset:208
	global_load_dwordx4 v[194:197], v41, s[16:17] offset:192
	global_load_dwordx4 v[202:205], v41, s[16:17] offset:272
	global_load_dwordx4 v[206:209], v41, s[16:17] offset:256
	global_load_dwordx4 v[210:213], v41, s[16:17] offset:336
	global_load_dwordx4 v[214:217], v41, s[16:17] offset:320
	global_load_dwordx4 v[218:221], v41, s[16:17] offset:400
	global_load_dwordx4 v[222:225], v41, s[16:17] offset:384
	global_load_dwordx4 v[226:229], v41, s[16:17] offset:464
	global_load_dwordx4 v[230:233], v41, s[16:17] offset:448
	v_mul_f32_e32 v97, v16, v97
	v_mul_f32_e32 v96, v16, v96
	v_mul_f32_e32 v101, v16, v101
	v_mul_f32_e32 v100, v16, v100
	v_mul_f32_e32 v105, v16, v105
	v_mul_f32_e32 v104, v16, v104
	v_mul_f32_e32 v109, v16, v109
	v_mul_f32_e32 v108, v16, v108
	v_mul_f32_e32 v113, v16, v113
	v_mul_f32_e32 v112, v16, v112
	v_mul_f32_e32 v95, v16, v95
	v_mul_f32_e32 v94, v16, v94
	v_mul_f32_e32 v87, v16, v87
	v_mul_f32_e32 v86, v16, v86
	v_mul_f32_e32 v79, v16, v79
	v_mul_f32_e32 v78, v16, v78
	v_mul_f32_e32 v71, v16, v71
	v_mul_f32_e32 v70, v16, v70
	v_mul_f32_e32 v63, v16, v63
	v_mul_f32_e32 v62, v16, v62
	v_mul_f32_e32 v51, v16, v51
	v_mul_f32_e32 v50, v16, v50
	v_mul_f32_e32 v43, v16, v43
	v_mul_f32_e32 v42, v16, v42
	v_mul_f32_e32 v34, v16, v34
	v_mul_f32_e32 v33, v16, v33
	v_mul_f32_e32 v29, v16, v29
	v_mul_f32_e32 v25, v16, v25
	v_mul_f32_e32 v21, v16, v21
	v_mul_f32_e32 v17, v16, v17
	v_mul_f32_e32 v14, v16, v14
	v_mul_f32_e32 v12, v16, v12
	s_waitcnt vmcnt(14)
	v_mov_b32_e32 v0, v156
	v_mov_b32_e32 v1, v157
	v_mov_b32_e32 v2, v158
	v_mov_b32_e32 v3, v159
	v_mov_b32_e32 v4, v160
	v_mov_b32_e32 v5, v161
	v_mov_b32_e32 v6, v162
	v_mov_b32_e32 v7, v163
	global_load_dwordx4 v[156:159], v41, s[16:17] offset:528
	global_load_dwordx4 v[160:163], v41, s[16:17] offset:512
	v_mul_f32_e32 v4, v4, v97
	v_mul_f32_e32 v5, v5, v96
	s_nop 0
	v_cvt_pk_bf16_f32 v96, v4, v5
	v_mul_f32_e32 v4, v16, v99
	v_mul_f32_e32 v4, v6, v4
	v_mul_f32_e32 v5, v16, v98
	v_mul_f32_e32 v5, v7, v5
	s_nop 0
	v_cvt_pk_bf16_f32 v97, v4, v5
	v_mul_f32_e32 v4, v16, v139
	v_mul_f32_e32 v0, v0, v4
	v_mul_f32_e32 v4, v16, v138
	v_mul_f32_e32 v1, v1, v4
	s_nop 0
	v_cvt_pk_bf16_f32 v98, v0, v1
	v_mul_f32_e32 v0, v16, v141
	v_mul_f32_e32 v1, v16, v140
	v_mul_f32_e32 v0, v2, v0
	v_mul_f32_e32 v1, v3, v1
	s_nop 0
	v_cvt_pk_bf16_f32 v99, v0, v1
	s_waitcnt vmcnt(14)
	v_mov_b32_e32 v0, v164
	v_mov_b32_e32 v1, v165
	v_mov_b32_e32 v2, v166
	v_mov_b32_e32 v3, v167
	v_mov_b32_e32 v4, v168
	v_mov_b32_e32 v5, v169
	v_mov_b32_e32 v6, v170
	v_mov_b32_e32 v7, v171
	global_load_dwordx4 v[164:167], v41, s[16:17] offset:592
	global_load_dwordx4 v[168:171], v41, s[16:17] offset:576
	v_mul_f32_e32 v4, v4, v101
	v_mul_f32_e32 v5, v5, v100
	s_nop 0
	v_cvt_pk_bf16_f32 v100, v4, v5
	v_mul_f32_e32 v4, v16, v103
	v_mul_f32_e32 v4, v6, v4
	v_mul_f32_e32 v5, v16, v102
	v_mul_f32_e32 v5, v7, v5
	s_nop 0
	v_cvt_pk_bf16_f32 v101, v4, v5
	v_mul_f32_e32 v4, v16, v135
	v_mul_f32_e32 v0, v0, v4
	v_mul_f32_e32 v4, v16, v134
	v_mul_f32_e32 v1, v1, v4
	s_nop 0
	v_cvt_pk_bf16_f32 v102, v0, v1
	v_mul_f32_e32 v0, v16, v137
	v_mul_f32_e32 v1, v16, v136
	v_mul_f32_e32 v0, v2, v0
	v_mul_f32_e32 v1, v3, v1
	s_nop 0
	v_cvt_pk_bf16_f32 v103, v0, v1
	s_waitcnt vmcnt(14)
	v_mov_b32_e32 v0, v172
	v_mov_b32_e32 v1, v173
	v_mov_b32_e32 v2, v174
	v_mov_b32_e32 v3, v175
	v_mov_b32_e32 v4, v176
	v_mov_b32_e32 v5, v177
	v_mov_b32_e32 v6, v178
	v_mov_b32_e32 v7, v179
	global_load_dwordx4 v[172:175], v41, s[16:17] offset:656
	global_load_dwordx4 v[176:179], v41, s[16:17] offset:640
	v_mul_f32_e32 v4, v4, v105
	v_mul_f32_e32 v5, v5, v104
	s_nop 0
	v_cvt_pk_bf16_f32 v104, v4, v5
	v_mul_f32_e32 v4, v16, v107
	v_mul_f32_e32 v4, v6, v4
	v_mul_f32_e32 v5, v16, v106
	v_mul_f32_e32 v5, v7, v5
	s_nop 0
	v_cvt_pk_bf16_f32 v105, v4, v5
	v_mul_f32_e32 v4, v16, v126
	v_mul_f32_e32 v0, v0, v4
	v_mul_f32_e32 v4, v16, v111
	v_mul_f32_e32 v1, v1, v4
	s_nop 0
	v_cvt_pk_bf16_f32 v106, v0, v1
	v_mul_f32_e32 v0, v16, v128
	v_mul_f32_e32 v1, v16, v127
	v_mul_f32_e32 v0, v2, v0
	v_mul_f32_e32 v1, v3, v1
	s_nop 0
	v_cvt_pk_bf16_f32 v107, v0, v1
	s_waitcnt vmcnt(14)
; __device__ __forceinline__ float bf_lo(unsigned u) { return __uint_as_float(u << 16); }
; __device__ __forceinline__ float bf_hi(unsigned u) { return __uint_as_float(u & 0xffff0000u); }
; __device__ __forceinline__ unsigned pk(float lo, float hi) { unsigned r; asm("s_nop 0\n\tv_cvt_pk_bf16_f32 %0, %1, %2" : "=v"(r) : "v"(lo), "v"(hi)); return r; }
; template <int DQK, bool MLA> ...
;     ...
; #pragma unroll
;         for (int d0 = 0; d0 < NS1; ++d0) {
;             const f32x4 ga = *(const f32x4*)(g1 + d0 * 16 + hi * 8), gb = *(const f32x4*)(g1 + d0 * 16 + hi * 8 + 4); u32x4 o;
;             o.x = pk(bf_lo(raw[d0].x) * rs1 * ga[0], bf_hi(raw[d0].x) * rs1 * ga[1]); o.y = pk(bf_lo(raw[d0].y) * rs1 * ga[2], bf_hi(raw[d0].y) * rs1 * ga[3]);
;             o.z = pk(bf_lo(raw[d0].z) * rs1 * gb[0], bf_hi(raw[d0].z) * rs1 * gb[1]); o.w = pk(bf_lo(raw[d0].w) * rs1 * gb[2], bf_hi(raw[d0].w) * rs1 * gb[3]);
;             qf[d0] = __builtin_bit_cast(bf16x8, o);
;         }
	v_mov_b32_e32 v0, v180
	v_mov_b32_e32 v1, v181
	v_mov_b32_e32 v2, v182
	v_mov_b32_e32 v3, v183
	v_mov_b32_e32 v4, v194
	v_mov_b32_e32 v5, v195
	v_mov_b32_e32 v6, v196
	v_mov_b32_e32 v7, v197
	global_load_dwordx4 v[180:183], v41, s[16:17] offset:720
	global_load_dwordx4 v[194:197], v41, s[16:17] offset:704
	v_mul_f32_e32 v4, v4, v109
	v_mul_f32_e32 v5, v5, v108
	s_nop 0
	v_cvt_pk_bf16_f32 v108, v4, v5
	v_mul_f32_e32 v4, v16, v110
	v_mul_f32_e32 v4, v6, v4
	v_mul_f32_e32 v5, v16, v129
	v_mul_f32_e32 v5, v7, v5
	s_nop 0
	v_cvt_pk_bf16_f32 v109, v4, v5
	v_mul_f32_e32 v4, v16, v131
	v_mul_f32_e32 v0, v0, v4
	v_mul_f32_e32 v4, v16, v130
	v_mul_f32_e32 v1, v1, v4
	s_nop 0
	v_cvt_pk_bf16_f32 v110, v0, v1
	v_mul_f32_e32 v0, v16, v133
	v_mul_f32_e32 v1, v16, v132
	v_mul_f32_e32 v0, v2, v0
	v_mul_f32_e32 v1, v3, v1
	s_nop 0
	v_cvt_pk_bf16_f32 v111, v0, v1
	s_waitcnt vmcnt(14)
	v_mov_b32_e32 v0, v202
	v_mov_b32_e32 v1, v203
	v_mov_b32_e32 v2, v204
	v_mov_b32_e32 v3, v205
	v_mov_b32_e32 v4, v206
	v_mov_b32_e32 v5, v207
	v_mov_b32_e32 v6, v208
	v_mov_b32_e32 v7, v209
	global_load_dwordx4 v[202:205], v41, s[16:17] offset:784
	global_load_dwordx4 v[206:209], v41, s[16:17] offset:768
	v_mul_f32_e32 v4, v4, v113
	v_mul_f32_e32 v5, v5, v112
	s_nop 0
	v_cvt_pk_bf16_f32 v112, v4, v5
	v_mul_f32_e32 v4, v16, v115
	v_mul_f32_e32 v4, v6, v4
	v_mul_f32_e32 v5, v16, v114
	v_mul_f32_e32 v5, v7, v5
	s_nop 0
	v_cvt_pk_bf16_f32 v113, v4, v5
	v_mul_f32_e32 v4, v16, v123
	v_mul_f32_e32 v0, v0, v4
	v_mul_f32_e32 v4, v16, v116
	v_mul_f32_e32 v1, v1, v4
	s_nop 0
	v_cvt_pk_bf16_f32 v114, v0, v1
	v_mul_f32_e32 v0, v16, v125
	v_mul_f32_e32 v1, v16, v124
	v_mul_f32_e32 v0, v2, v0
	v_mul_f32_e32 v1, v3, v1
	s_nop 0
	v_cvt_pk_bf16_f32 v115, v0, v1
	s_waitcnt vmcnt(14)
	v_mov_b32_e32 v0, v210
	v_mov_b32_e32 v1, v211
	v_mov_b32_e32 v2, v212
	v_mov_b32_e32 v3, v213
	v_mov_b32_e32 v4, v214
	v_mov_b32_e32 v5, v215
	v_mov_b32_e32 v6, v216
	v_mov_b32_e32 v7, v217
	global_load_dwordx4 v[210:213], v41, s[16:17] offset:848
	global_load_dwordx4 v[214:217], v41, s[16:17] offset:832
	v_mul_f32_e32 v4, v4, v95
	v_mul_f32_e32 v5, v5, v94
	s_nop 0
	v_cvt_pk_bf16_f32 v116, v4, v5
	v_mul_f32_e32 v4, v16, v118
	v_mul_f32_e32 v4, v6, v4
	v_mul_f32_e32 v5, v16, v117
	v_mul_f32_e32 v5, v7, v5
	s_nop 0
	v_cvt_pk_bf16_f32 v117, v4, v5
	v_mul_f32_e32 v4, v16, v120
	v_mul_f32_e32 v0, v0, v4
	v_mul_f32_e32 v4, v16, v119
	v_mul_f32_e32 v1, v1, v4
	s_nop 0
	v_cvt_pk_bf16_f32 v118, v0, v1
	v_mul_f32_e32 v0, v16, v122
	v_mul_f32_e32 v1, v16, v121
	v_mul_f32_e32 v0, v2, v0
	v_mul_f32_e32 v1, v3, v1
	s_nop 0
	v_cvt_pk_bf16_f32 v119, v0, v1
	s_waitcnt vmcnt(14)
	v_mov_b32_e32 v0, v218
	v_mov_b32_e32 v1, v219
	v_mov_b32_e32 v2, v220
	v_mov_b32_e32 v3, v221
	v_mov_b32_e32 v4, v222
	v_mov_b32_e32 v5, v223
	v_mov_b32_e32 v6, v224
	v_mov_b32_e32 v7, v225
	global_load_dwordx4 v[218:221], v41, s[16:17] offset:912
	global_load_dwordx4 v[222:225], v41, s[16:17] offset:896
	v_mul_f32_e32 v4, v4, v87
	v_mul_f32_e32 v5, v5, v86
	s_nop 0
	v_cvt_pk_bf16_f32 v120, v4, v5
	v_mul_f32_e32 v4, v16, v89
	v_mul_f32_e32 v4, v6, v4
	v_mul_f32_e32 v5, v16, v88
	v_mul_f32_e32 v5, v7, v5
	s_nop 0
	v_cvt_pk_bf16_f32 v121, v4, v5
	v_mul_f32_e32 v4, v16, v91
	v_mul_f32_e32 v0, v0, v4
	v_mul_f32_e32 v4, v16, v90
	v_mul_f32_e32 v1, v1, v4
	s_nop 0
	v_cvt_pk_bf16_f32 v122, v0, v1
	v_mul_f32_e32 v0, v16, v93
	v_mul_f32_e32 v1, v16, v92
	v_mul_f32_e32 v0, v2, v0
	v_mul_f32_e32 v1, v3, v1
	s_nop 0
	v_cvt_pk_bf16_f32 v123, v0, v1
	s_waitcnt vmcnt(14)
	v_mov_b32_e32 v0, v226
	v_mov_b32_e32 v1, v227
	v_mov_b32_e32 v2, v228
	v_mov_b32_e32 v3, v229
	v_mov_b32_e32 v4, v230
	v_mov_b32_e32 v5, v231
	v_mov_b32_e32 v6, v232
	v_mov_b32_e32 v7, v233
	global_load_dwordx4 v[226:229], v41, s[16:17] offset:976
	global_load_dwordx4 v[230:233], v41, s[16:17] offset:960
	v_mul_f32_e32 v4, v4, v79
	v_mul_f32_e32 v5, v5, v78
	s_nop 0
	v_cvt_pk_bf16_f32 v124, v4, v5
	v_mul_f32_e32 v4, v16, v81
	v_mul_f32_e32 v4, v6, v4
	v_mul_f32_e32 v5, v16, v80
	v_mul_f32_e32 v5, v7, v5
	s_nop 0
	v_cvt_pk_bf16_f32 v125, v4, v5
	v_mul_f32_e32 v4, v16, v83
	v_mul_f32_e32 v0, v0, v4
	v_mul_f32_e32 v4, v16, v82
	v_mul_f32_e32 v1, v1, v4
	s_nop 0
	v_cvt_pk_bf16_f32 v126, v0, v1
	v_mul_f32_e32 v0, v16, v85
	v_mul_f32_e32 v1, v16, v84
	v_mul_f32_e32 v0, v2, v0
	v_mul_f32_e32 v1, v3, v1
	s_nop 0
	v_cvt_pk_bf16_f32 v127, v0, v1
	s_waitcnt vmcnt(14)
	v_mov_b32_e32 v0, v156
	v_mov_b32_e32 v1, v157
	v_mov_b32_e32 v2, v158
	v_mov_b32_e32 v3, v159
	v_mov_b32_e32 v4, v160
	v_mov_b32_e32 v5, v161
	v_mov_b32_e32 v6, v162
	v_mov_b32_e32 v7, v163
	v_mul_f32_e32 v4, v4, v71
	v_mul_f32_e32 v5, v5, v70
	s_nop 0
	v_cvt_pk_bf16_f32 v128, v4, v5
	v_mul_f32_e32 v4, v16, v73
	v_mul_f32_e32 v4, v6, v4
	v_mul_f32_e32 v5, v16, v72
	v_mul_f32_e32 v5, v7, v5
	s_nop 0
	v_cvt_pk_bf16_f32 v129, v4, v5
	v_mul_f32_e32 v4, v16, v75
	v_mul_f32_e32 v0, v0, v4
	v_mul_f32_e32 v4, v16, v74
	v_mul_f32_e32 v1, v1, v4
	s_nop 0
	v_cvt_pk_bf16_f32 v130, v0, v1
	v_mul_f32_e32 v0, v16, v77
	v_mul_f32_e32 v1, v16, v76
	v_mul_f32_e32 v0, v2, v0
	v_mul_f32_e32 v1, v3, v1
	s_nop 0
	v_cvt_pk_bf16_f32 v131, v0, v1
	s_waitcnt vmcnt(12)
	v_mov_b32_e32 v0, v164
	v_mov_b32_e32 v1, v165
	v_mov_b32_e32 v2, v166
	v_mov_b32_e32 v3, v167
	v_mov_b32_e32 v4, v168
	v_mov_b32_e32 v5, v169
	v_mov_b32_e32 v6, v170
	v_mov_b32_e32 v7, v171
	v_mul_f32_e32 v4, v4, v63
	v_mul_f32_e32 v5, v5, v62
	s_nop 0
	v_cvt_pk_bf16_f32 v132, v4, v5
	v_mul_f32_e32 v4, v16, v65
	v_mul_f32_e32 v4, v6, v4
	v_mul_f32_e32 v5, v16, v64
	v_mul_f32_e32 v5, v7, v5
	s_nop 0
	v_cvt_pk_bf16_f32 v133, v4, v5
	v_mul_f32_e32 v4, v16, v67
	v_mul_f32_e32 v0, v0, v4
	v_mul_f32_e32 v4, v16, v66
	v_mul_f32_e32 v1, v1, v4
	s_nop 0
	v_cvt_pk_bf16_f32 v134, v0, v1
	v_mul_f32_e32 v0, v16, v69
	v_mul_f32_e32 v1, v16, v68
	v_mul_f32_e32 v0, v2, v0
	v_mul_f32_e32 v1, v3, v1
	s_nop 0
	v_cvt_pk_bf16_f32 v135, v0, v1
	s_waitcnt vmcnt(10)
; __device__ __forceinline__ float bf_lo(unsigned u) { return __uint_as_float(u << 16); }
; __device__ __forceinline__ float bf_hi(unsigned u) { return __uint_as_float(u & 0xffff0000u); }
; __device__ __forceinline__ unsigned pk(float lo, float hi) { unsigned r; asm("s_nop 0\n\tv_cvt_pk_bf16_f32 %0, %1, %2" : "=v"(r) : "v"(lo), "v"(hi)); return r; }
; template <int DQK, bool MLA> ...
;     ...
;         const float rs1 = __builtin_amdgcn_rsqf(s1 * (MLA ? (1.f / 128.f) : (1.f / 256.f)) + EPS) * qscale;
; #pragma unroll
;         for (int d0 = 0; d0 < NS1; ++d0) {
;             const f32x4 ga = *(const f32x4*)(g1 + d0 * 16 + hi * 8), gb = *(const f32x4*)(g1 + d0 * 16 + hi * 8 + 4); u32x4 o;
;             o.x = pk(bf_lo(raw[d0].x) * rs1 * ga[0], bf_hi(raw[d0].x) * rs1 * ga[1]); o.y = pk(bf_lo(raw[d0].y) * rs1 * ga[2], bf_hi(raw[d0].y) * rs1 * ga[3]);
;             o.z = pk(bf_lo(raw[d0].z) * rs1 * gb[0], bf_hi(raw[d0].z) * rs1 * gb[1]); o.w = pk(bf_lo(raw[d0].w) * rs1 * gb[2], bf_hi(raw[d0].w) * rs1 * gb[3]);
;             qf[d0] = __builtin_bit_cast(bf16x8, o);
;     ...
;     auto load_tile = [&](int t) {
; #pragma unroll
;         for (int i = 0; i < NKC; ++i) { const int c = tid + NTHR * i, row = c / CPR, cc = c % CPR; const size_t key = (size_t)t * 64 + row;
;             const bf16_t* src = (MLA && cc >= 16) ? (Kb + key * 64 + (cc - 16) * 8) : (Ka + key * kapitch + cc * 8);
;             kreg[i] = *(const u32x4*)src; }
;         const bf16_t* vs = Vt + (size_t)t * 9216;
;         vreg[0] = *(const u32x4*)(vs + tid * 8); vreg[1] = *(const u32x4*)(vs + (tid + 512) * 8);
;         if (tid < 128) vreg[2] = *(const u32x4*)(vs + (tid + 1024) * 8);
	v_mov_b32_e32 v0, v172
	v_mov_b32_e32 v1, v173
	v_mov_b32_e32 v2, v174
	v_mov_b32_e32 v3, v175
	v_mov_b32_e32 v4, v176
	v_mov_b32_e32 v5, v177
	v_mov_b32_e32 v6, v178
	v_mov_b32_e32 v7, v179
	v_mul_f32_e32 v4, v51, v4
	v_mul_f32_e32 v5, v50, v5
	s_nop 0
	v_cvt_pk_bf16_f32 v136, v4, v5
	v_mul_f32_e32 v4, v16, v57
	v_mul_f32_e32 v4, v4, v6
	v_mul_f32_e32 v5, v16, v53
	v_mul_f32_e32 v5, v5, v7
	s_nop 0
	v_cvt_pk_bf16_f32 v137, v4, v5
	v_mul_f32_e32 v4, v16, v59
	v_mul_f32_e32 v0, v4, v0
	v_mul_f32_e32 v4, v16, v58
	v_mul_f32_e32 v1, v4, v1
	s_nop 0
	v_cvt_pk_bf16_f32 v138, v0, v1
	v_mul_f32_e32 v0, v16, v61
	v_mul_f32_e32 v1, v16, v60
	v_mul_f32_e32 v0, v0, v2
	v_mul_f32_e32 v1, v1, v3
	s_nop 0
	v_cvt_pk_bf16_f32 v139, v0, v1
	s_waitcnt vmcnt(8)
	v_mov_b32_e32 v0, v180
	v_mov_b32_e32 v1, v181
	v_mov_b32_e32 v2, v182
	v_mov_b32_e32 v3, v183
	v_mov_b32_e32 v4, v194
	v_mov_b32_e32 v5, v195
	v_mov_b32_e32 v6, v196
	v_mov_b32_e32 v7, v197
	v_mul_f32_e32 v4, v43, v4
	v_mul_f32_e32 v5, v42, v5
	s_nop 0
	v_cvt_pk_bf16_f32 v140, v4, v5
	v_mul_f32_e32 v4, v16, v45
	v_mul_f32_e32 v4, v4, v6
	v_mul_f32_e32 v5, v16, v44
	v_mul_f32_e32 v5, v5, v7
	s_nop 0
	v_cvt_pk_bf16_f32 v141, v4, v5
	v_mul_f32_e32 v4, v16, v47
	v_mul_f32_e32 v0, v4, v0
	v_mul_f32_e32 v4, v16, v46
	v_mul_f32_e32 v1, v4, v1
	s_nop 0
	v_cvt_pk_bf16_f32 v142, v0, v1
	v_mul_f32_e32 v0, v16, v49
	v_mul_f32_e32 v1, v16, v48
	v_mul_f32_e32 v0, v0, v2
	v_mul_f32_e32 v1, v1, v3
	s_nop 0
	v_cvt_pk_bf16_f32 v143, v0, v1
	s_waitcnt vmcnt(6)
	v_mov_b32_e32 v0, v202
	v_mov_b32_e32 v1, v203
	v_mov_b32_e32 v2, v204
	v_mov_b32_e32 v3, v205
	v_mov_b32_e32 v4, v206
	v_mov_b32_e32 v5, v207
	v_mov_b32_e32 v6, v208
	v_mov_b32_e32 v7, v209
	v_mul_f32_e32 v4, v34, v4
	v_mul_f32_e32 v5, v33, v5
	s_nop 0
	v_cvt_pk_bf16_f32 v144, v4, v5
	v_mul_f32_e32 v4, v16, v36
	v_mul_f32_e32 v4, v4, v6
	v_mul_f32_e32 v5, v16, v35
	v_mul_f32_e32 v5, v5, v7
	s_nop 0
	v_cvt_pk_bf16_f32 v145, v4, v5
	v_mul_f32_e32 v4, v16, v38
	v_mul_f32_e32 v0, v4, v0
	v_mul_f32_e32 v4, v16, v37
	v_mul_f32_e32 v1, v4, v1
	s_nop 0
	v_cvt_pk_bf16_f32 v146, v0, v1
	v_mul_f32_e32 v0, v16, v40
	v_mul_f32_e32 v1, v16, v39
	v_mul_f32_e32 v0, v0, v2
	v_mul_f32_e32 v1, v1, v3
	s_nop 0
	v_cvt_pk_bf16_f32 v147, v0, v1
	s_waitcnt vmcnt(4)
	v_mov_b32_e32 v0, v210
	v_mov_b32_e32 v1, v211
	v_mov_b32_e32 v2, v212
	v_mov_b32_e32 v3, v213
	v_mov_b32_e32 v4, v214
	v_mov_b32_e32 v5, v215
	v_mov_b32_e32 v6, v216
	v_mov_b32_e32 v7, v217
	v_mul_f32_e32 v4, v29, v4
	v_mul_f32_e32 v5, v25, v5
	s_nop 0
	v_cvt_pk_bf16_f32 v148, v4, v5
	v_mul_f32_e32 v4, v16, v30
	v_mul_f32_e32 v4, v4, v6
	v_mul_f32_e32 v5, v16, v26
	v_mul_f32_e32 v5, v5, v7
	s_nop 0
	v_cvt_pk_bf16_f32 v149, v4, v5
	v_mul_f32_e32 v4, v16, v31
	v_mul_f32_e32 v0, v4, v0
	v_mul_f32_e32 v4, v16, v27
	v_mul_f32_e32 v1, v4, v1
	s_nop 0
	v_cvt_pk_bf16_f32 v150, v0, v1
	v_mul_f32_e32 v0, v16, v32
	v_mul_f32_e32 v1, v16, v28
	v_mul_f32_e32 v0, v0, v2
	v_mul_f32_e32 v1, v1, v3
	s_nop 0
	v_cvt_pk_bf16_f32 v151, v0, v1
	v_add_u32_e32 v30, s33, v56
	s_waitcnt vmcnt(2)
	v_mov_b32_e32 v0, v218
	v_mov_b32_e32 v1, v219
	v_mov_b32_e32 v2, v220
	v_mov_b32_e32 v3, v221
	v_mov_b32_e32 v4, v222
	v_mov_b32_e32 v5, v223
	v_mov_b32_e32 v6, v224
	v_mov_b32_e32 v7, v225
	v_mul_f32_e32 v4, v21, v4
	v_mul_f32_e32 v5, v17, v5
	s_nop 0
	v_cvt_pk_bf16_f32 v152, v4, v5
	v_mul_f32_e32 v4, v16, v22
	v_mul_f32_e32 v4, v4, v6
	v_mul_f32_e32 v5, v16, v18
	v_mul_f32_e32 v5, v5, v7
	s_nop 0
	v_cvt_pk_bf16_f32 v153, v4, v5
	v_mul_f32_e32 v4, v16, v23
	v_mul_f32_e32 v0, v4, v0
	v_mul_f32_e32 v4, v16, v19
	v_mul_f32_e32 v1, v4, v1
	s_nop 0
	v_cvt_pk_bf16_f32 v154, v0, v1
	v_mul_f32_e32 v0, v16, v24
	v_mul_f32_e32 v1, v16, v20
	v_mul_f32_e32 v0, v0, v2
	v_mul_f32_e32 v1, v1, v3
	s_nop 0
	v_cvt_pk_bf16_f32 v155, v0, v1
	s_waitcnt vmcnt(0)
	v_mov_b32_e32 v0, v226
	v_mov_b32_e32 v1, v227
	v_mov_b32_e32 v2, v228
	v_mov_b32_e32 v3, v229
	v_mov_b32_e32 v4, v230
	v_mov_b32_e32 v5, v231
	v_mov_b32_e32 v6, v232
	v_mov_b32_e32 v7, v233
	v_mul_f32_e32 v4, v14, v4
	v_mul_f32_e32 v5, v12, v5
	s_nop 0
	v_cvt_pk_bf16_f32 v156, v4, v5
	v_mul_f32_e32 v4, v16, v15
	v_mul_f32_e32 v4, v4, v6
	v_mul_f32_e32 v5, v16, v13
	v_mul_f32_e32 v5, v5, v7
	s_nop 0
	v_cvt_pk_bf16_f32 v157, v4, v5
	v_mul_f32_e32 v4, v16, v10
	v_mul_f32_e32 v0, v4, v0
	v_mul_f32_e32 v4, v16, v8
	v_mul_f32_e32 v1, v4, v1
	s_nop 0
	v_cvt_pk_bf16_f32 v158, v0, v1
	v_mul_f32_e32 v0, v16, v11
	v_mul_f32_e32 v0, v0, v2
	v_mul_f32_e32 v1, v16, v9
	v_mul_f32_e32 v1, v1, v3
	s_nop 0
	v_cvt_pk_bf16_f32 v159, v0, v1
	v_ashrrev_i32_e32 v0, 31, v30
	v_lshrrev_b32_e32 v0, 27, v0
	v_add_u32_e32 v0, v30, v0
	v_ashrrev_i32_e32 v20, 5, v0
	v_and_b32_e32 v0, 0xffffffe0, v0
	v_sub_u32_e32 v31, v30, v0
	v_ashrrev_i32_e32 v21, 31, v20
	v_lshlrev_b64 v[0:1], 12, v[20:21]
	v_lshlrev_b32_e32 v2, 3, v31
	v_lshl_add_u64 v[4:5], s[4:5], 0, v[0:1]
	v_ashrrev_i32_e32 v3, 31, v2
	v_lshl_add_u64 v[4:5], v[2:3], 1, v[4:5]
	global_load_dwordx4 v[160:163], v[4:5], off
	v_add_u32_e32 v4, 0x200, v30
	v_ashrrev_i32_e32 v5, 31, v4
	v_lshrrev_b32_e32 v5, 27, v5
	v_add_u32_e32 v5, v4, v5
	v_ashrrev_i32_e32 v22, 5, v5
	v_and_b32_e32 v5, 0xffffffe0, v5
	v_sub_u32_e32 v21, v4, v5
	v_ashrrev_i32_e32 v23, 31, v22
	v_lshlrev_b64 v[4:5], 12, v[22:23]
	v_lshlrev_b32_e32 v6, 3, v21
	v_lshl_add_u64 v[8:9], s[4:5], 0, v[4:5]
	v_ashrrev_i32_e32 v7, 31, v6
	v_lshl_add_u64 v[8:9], v[6:7], 1, v[8:9]
	global_load_dwordx4 v[164:167], v[8:9], off
	v_add_u32_e32 v8, 0x400, v30
	v_ashrrev_i32_e32 v9, 31, v8
	v_lshrrev_b32_e32 v9, 27, v9
	v_add_u32_e32 v9, v8, v9
	v_ashrrev_i32_e32 v24, 5, v9
	v_and_b32_e32 v9, 0xffffffe0, v9
	v_sub_u32_e32 v23, v8, v9
	v_ashrrev_i32_e32 v25, 31, v24
	v_lshlrev_b64 v[8:9], 12, v[24:25]
	v_lshlrev_b32_e32 v10, 3, v23
	v_lshl_add_u64 v[12:13], s[4:5], 0, v[8:9]
	v_ashrrev_i32_e32 v11, 31, v10
	v_lshl_add_u64 v[12:13], v[10:11], 1, v[12:13]
	global_load_dwordx4 v[168:171], v[12:13], off
	v_add_u32_e32 v12, 0x600, v30
	v_ashrrev_i32_e32 v13, 31, v12
	v_lshrrev_b32_e32 v13, 27, v13
	v_add_u32_e32 v13, v12, v13
	v_ashrrev_i32_e32 v26, 5, v13
	v_and_b32_e32 v13, 0xffffffe0, v13
	v_sub_u32_e32 v25, v12, v13
	v_ashrrev_i32_e32 v27, 31, v26
	v_lshlrev_b64 v[12:13], 12, v[26:27]
	v_lshlrev_b32_e32 v14, 3, v25
	v_lshl_add_u64 v[16:17], s[4:5], 0, v[12:13]
	v_ashrrev_i32_e32 v15, 31, v14
	v_lshl_add_u64 v[16:17], v[14:15], 1, v[16:17]
	global_load_dwordx4 v[172:175], v[16:17], off
	v_lshlrev_b32_e32 v16, 3, v30
	v_ashrrev_i32_e32 v17, 31, v16
	v_lshl_add_u64 v[18:19], v[16:17], 1, s[30:31]
	global_load_dwordx4 v[176:179], v[18:19], off
	v_add_u32_e32 v18, 0x1000, v16
	v_ashrrev_i32_e32 v19, 31, v18
	v_lshl_add_u64 v[28:29], v[18:19], 1, s[30:31]
	global_load_dwordx4 v[180:183], v[28:29], off
	v_cmp_gt_i32_e64 s[4:5], s3, v30
	v_add_u32_e32 v28, 0x2000, v16
	s_and_saveexec_b64 s[34:35], s[4:5]
	s_cbranch_execz .LBB0_1065
	v_ashrrev_i32_e32 v29, 31, v28
	v_lshl_add_u64 v[32:33], v[28:29], 1, s[30:31]
	global_load_dwordx4 v[184:187], v[32:33], off
